# v47 + final phase: the 768 fold rows taken by waves 0..2 of every workgroup instead of all waves of workgroups 0..95
# speedup vs baseline: 1.0131x; 1.0002x over previous
; #define PARAMS const __attribute__((address_space(4))) Params&
; #define BIDX bid_opaque()
; #define GDIM gdim_opaque()
; DI void final_phase(PARAMS P, int wave, int lane) {
;     const int gw = BIDX * 8 + wave, NGW = GDIM * 8;
;     const float* X = (const float*)(P.ws + WS_X);
;     f32x4 gv[4];
; #pragma unroll
;     for (int j = 0; j < 4; ++j) gv[j] = ((const f32x4*)P.in[28])[lane + 64 * j];
;     for (int row = gw; row < MTOT; row += NGW) {
.LBB0_924:
	s_and_b64 vcc, exec, s[68:69]
	s_cbranch_vccz .LBB0_940
	s_waitcnt vmcnt(0)
	v_mov_b32_e32 v0, v228
	v_mov_b32_e32 v1, v228
	s_nop 0
	v_readfirstlane_b32 s0, v1
	s_ashr_i32 s1, s0, 6
	s_mov_b32 s0, s82
	s_lshl_b32 s2, s0, 3
	s_add_i32 s8, s2, s1
	s_mov_b32 s101, 0x82ff
	s_mov_b32 s100, 0
	s_cmp_lg_u32 s92, 0x100
	s_cbranch_scc1 .Lfin_setup_done
	s_movk_i32 s101, 0x7fff
	s_cmp_gt_u32 s1, 2
	s_cbranch_scc1 .Lfin_setup_done
	s_lshl_b32 s99, s1, 8
	s_add_i32 s99, s99, s82
	s_add_i32 s99, s99, 0x8000
	s_mov_b32 s100, 1
.Lfin_setup_done:
	s_mov_b32 s0, s92
	s_cmp_gt_i32 s8, 0x82ff
	s_cbranch_scc1 .LBB0_939
	s_load_dwordx4 s[4:7], s[18:19], 0xe0
	s_load_dwordx2 s[10:11], s[18:19], 0xf0
	s_waitcnt vmcnt(0)
	v_and_b32_e32 v16, 63, v0
	v_lshlrev_b32_e32 v32, 4, v16
	s_lshl_b32 s0, s0, 3
	s_waitcnt lgkmcnt(0)
	global_load_dwordx4 v[0:3], v32, s[4:5]
	global_load_dwordx4 v[4:7], v32, s[4:5] offset:1024
	global_load_dwordx4 v[8:11], v32, s[4:5] offset:2048
	global_load_dwordx4 v[12:15], v32, s[4:5] offset:3072
	s_add_u32 s1, s6, 0x8000000
	v_lshl_add_u64 v[34:35], s[10:11], 0, v[32:33]
	s_mov_b64 s[4:5], 0x1c67a000
	s_addc_u32 s2, s7, 0
	v_lshl_add_u64 v[36:37], v[34:35], 0, s[4:5]
	v_lshlrev_b32_e32 v32, 4, v16
	s_branch .LBB0_929

; DI void final_phase(PARAMS P, int wave, int lane) {
;     ...
;     for (int row = gw; row < MTOT; row += NGW) {
.LBB0_928:
	s_add_i32 s8, s8, s0
	s_cmp_gt_i32 s8, s101
	s_cbranch_scc0 .LBB0_929
	s_cmp_eq_u32 s100, 1
	s_cbranch_scc0 .LBB0_939
	s_mov_b32 s100, 0
	s_mov_b32 s8, s99
